# dense: K-fragment read pairs split around their QK^T MFMA pair (one LDS read per MFMA gap)
# speedup vs baseline: 1.0249x; 1.0050x over previous
; #define SBAR() __builtin_amdgcn_sched_barrier(0)
; #define KRD(f, d0, kb) asm volatile("ds_read_b128 %0, %2 offset:%3\n\tds_read_b128 %1, %2 offset:%4" : "=&v"(f.a), "=&v"(f.b) : "v"((kb) + koff[(d0) & 3]), "i"(((d0) >> 2) * 128), "i"(((d0) >> 2) * 128 + 8192) : "memory")
; #define QMM(f, d0) do { pA0 = __builtin_amdgcn_mfma_f32_32x32x16_bf16(f.a, qr[d0], pA0, 0, 0, 0); pA1 = __builtin_amdgcn_mfma_f32_32x32x16_bf16(f.b, qr[d0], pA1, 0, 0, 0); } while (0)
; #define LW(n) do { asm volatile("s_waitcnt lgkmcnt(" #n ")" ::: "memory"); SBAR(); } while (0)
;     ...
;         LW(10); pA0 = __builtin_amdgcn_mfma_f32_32x32x16_bf16(k0_.a, qr[0], negm, 0, 0, 0); pA1 = __builtin_amdgcn_mfma_f32_32x32x16_bf16(k0_.b, qr[0], negm, 0, 0, 0); SBAR(); KRD(k0_, 2, kb_);
;     ...
;         pA0 = f32x16{}; pA1 = f32x16{};
;         LW(10); QMM(k0_, 0); SBAR(); KRD(k0_, 2, kb_);
;     ...
;         LW(10); QMM(k1_, 1); SBAR(); KRD(k1_, 3, kb_);
;         LW(4);  pv_mm(o[0], fa_, pa0, pa1, pa2, pa3); SBAR(); pv_rd<1>(fb_, vb_);
;         LW(10); QMM(k0_, 2); SBAR(); KRD(k0_, 4, kb_);
;         LW(10); QMM(k1_, 3); SBAR(); KRD(k1_, 5, kb_);
;         LW(4);  pv_mm(o[1], fb_, pa0, pa1, pa2, pa3); SBAR(); pv_rd<2>(fa_, vb_);
;         LW(10); QMM(k0_, 4); SBAR(); KRD(k0_, 6, kb_);
;         LW(10); QMM(k1_, 5); SBAR(); KRD(k1_, 7, kb_);
;         LW(4);  pv_mm(o[2], fa_, pa0, pa1, pa2, pa3); SBAR(); pv_rd<3>(fb_, vb_);
;         LW(10); QMM(k0_, 6); SBAR();
;         LW(8);  QMM(k1_, 7); SBAR();
;         LW(0);  pv_mm(o[3], fb_, pa0, pa1, pa2, pa3);
.LBB0_69:
	s_waitcnt lgkmcnt(10)
	v_mfma_f32_32x32x16_bf16 v[98:113], v[82:85], v[158:161], v[66:81]
	v_add_u32_e32 v217, s87, v237
	ds_read_b128 v[250:253], v217 offset:0x2000
	v_mfma_f32_32x32x16_bf16 v[82:97], v[202:205], v[158:161], v[66:81]
	ds_read_b128 v[202:205], v217 offset:0
	s_waitcnt lgkmcnt(10)
	v_mfma_f32_32x32x16_bf16 v[98:113], v[198:201], v[154:157], v[98:113]
	v_add_u32_e32 v206, s87, v236
	ds_read_b128 v[198:201], v206 offset:0x2000
	v_mfma_f32_32x32x16_bf16 v[82:97], v[194:197], v[154:157], v[82:97]
	ds_read_b128 v[194:197], v206 offset:0
	s_waitcnt lgkmcnt(4)
	v_mfma_f32_32x32x16_bf16 v[2:17], v[174:177], v[190:193], v[2:17]
	ds_read_b64_tr_b16 v[190:191], v246 offset:0x3200
	ds_read_b64_tr_b16 v[192:193], v246 offset:0x3a00
	v_mfma_f32_32x32x16_bf16 v[2:17], v[170:173], v[186:189], v[2:17]
	ds_read_b64_tr_b16 v[186:187], v246 offset:0x2200
	ds_read_b64_tr_b16 v[188:189], v246 offset:0x2a00
	v_mfma_f32_32x32x16_bf16 v[2:17], v[166:169], v[182:185], v[2:17]
	ds_read_b64_tr_b16 v[182:183], v246 offset:0x1200
	ds_read_b64_tr_b16 v[184:185], v246 offset:0x1a00
	v_mfma_f32_32x32x16_bf16 v[2:17], v[162:165], v[178:181], v[2:17]
	ds_read_b64_tr_b16 v[178:179], v246 offset:0x200
	ds_read_b64_tr_b16 v[180:181], v246 offset:0xa00
	s_waitcnt lgkmcnt(10)
	v_mfma_f32_32x32x16_bf16 v[98:113], v[202:205], v[150:153], v[98:113]
	ds_read_b128 v[202:205], v248 offset:0x80
	v_mfma_f32_32x32x16_bf16 v[82:97], v[250:253], v[150:153], v[82:97]
	ds_read_b128 v[250:253], v248 offset:0x2080
	s_waitcnt lgkmcnt(10)
	v_mfma_f32_32x32x16_bf16 v[98:113], v[194:197], v[146:149], v[98:113]
	ds_read_b128 v[194:197], v247 offset:0x80
	v_mfma_f32_32x32x16_bf16 v[82:97], v[198:201], v[146:149], v[82:97]
	ds_read_b128 v[198:201], v247 offset:0x2080
	s_waitcnt lgkmcnt(4)
	v_mfma_f32_32x32x16_bf16 v[50:65], v[174:177], v[178:181], v[50:65]
	ds_read_b64_tr_b16 v[178:179], v246 offset:0x400
	ds_read_b64_tr_b16 v[180:181], v246 offset:0xc00
	v_mfma_f32_32x32x16_bf16 v[50:65], v[170:173], v[182:185], v[50:65]
	ds_read_b64_tr_b16 v[182:183], v246 offset:0x1400
	ds_read_b64_tr_b16 v[184:185], v246 offset:0x1c00
	v_mfma_f32_32x32x16_bf16 v[50:65], v[166:169], v[186:189], v[50:65]
	ds_read_b64_tr_b16 v[186:187], v246 offset:0x2400
	ds_read_b64_tr_b16 v[188:189], v246 offset:0x2c00
	v_mfma_f32_32x32x16_bf16 v[50:65], v[162:165], v[190:193], v[50:65]
	ds_read_b64_tr_b16 v[190:191], v246 offset:0x3400
	ds_read_b64_tr_b16 v[192:193], v246 offset:0x3c00
	s_waitcnt lgkmcnt(10)
	v_mfma_f32_32x32x16_bf16 v[98:113], v[202:205], v[142:145], v[98:113]
	ds_read_b128 v[202:205], v217 offset:0x80
	v_mfma_f32_32x32x16_bf16 v[82:97], v[250:253], v[142:145], v[82:97]
	ds_read_b128 v[248:251], v217 offset:0x2080
	s_waitcnt lgkmcnt(10)
	v_mfma_f32_32x32x16_bf16 v[98:113], v[194:197], v[138:141], v[98:113]
	ds_read_b128 v[194:197], v206 offset:0x80
	v_mfma_f32_32x32x16_bf16 v[82:97], v[198:201], v[138:141], v[82:97]
	ds_read_b128 v[198:201], v206 offset:0x2080
	s_waitcnt lgkmcnt(4)
	v_mfma_f32_32x32x16_bf16 v[34:49], v[174:177], v[178:181], v[34:49]
	ds_read_b64_tr_b16 v[178:179], v246 offset:0x600
	ds_read_b64_tr_b16 v[180:181], v246 offset:0xe00
	v_mfma_f32_32x32x16_bf16 v[34:49], v[170:173], v[182:185], v[34:49]
	ds_read_b64_tr_b16 v[182:183], v246 offset:0x1600
	ds_read_b64_tr_b16 v[184:185], v246 offset:0x1e00
	v_mfma_f32_32x32x16_bf16 v[34:49], v[166:169], v[186:189], v[34:49]
	ds_read_b64_tr_b16 v[186:187], v246 offset:0x2600
	ds_read_b64_tr_b16 v[188:189], v246 offset:0x2e00
	v_mfma_f32_32x32x16_bf16 v[34:49], v[162:165], v[190:193], v[34:49]
	ds_read_b64_tr_b16 v[190:191], v246 offset:0x3600
	ds_read_b64_tr_b16 v[192:193], v246 offset:0x3e00
	s_waitcnt lgkmcnt(10)
	v_mfma_f32_32x32x16_bf16 v[98:113], v[202:205], v[134:137], v[98:113]
	v_mfma_f32_32x32x16_bf16 v[82:97], v[248:251], v[134:137], v[82:97]
	s_waitcnt lgkmcnt(8)
	v_mfma_f32_32x32x16_bf16 v[98:113], v[194:197], v[130:133], v[98:113]
	v_mfma_f32_32x32x16_bf16 v[82:97], v[198:201], v[130:133], v[82:97]
	s_waitcnt lgkmcnt(0)
	v_mfma_f32_32x32x16_bf16 v[18:33], v[174:177], v[178:181], v[18:33]
	s_mov_b64 s[86:87], -1
	s_and_b64 vcc, exec, s[0:1]
	v_mfma_f32_32x32x16_bf16 v[18:33], v[170:173], v[182:185], v[18:33]
	v_mfma_f32_32x32x16_bf16 v[18:33], v[166:169], v[186:189], v[18:33]
	v_mfma_f32_32x32x16_bf16 v[18:33], v[162:165], v[190:193], v[18:33]
	s_cbranch_vccz .LBB0_72
	s_waitcnt lgkmcnt(0)
	s_barrier
	s_cbranch_execz .LBB0_73
